# v92 + SSM-table job inner product loop in scalar mul/fma form (24 VALU per 4 p instead of 28 with half-used packed ops)
# speedup vs baseline: 1.0018x; 1.0013x over previous
.LBB0_88:
	v_add_u32_e32 v9, s4, v4
	ds_read2_b64 v[10:13], v7 offset1:33
	ds_read2_b64 v[14:17], v8 offset1:16
	ds_read2_b64 v[18:21], v7 offset0:66 offset1:99
	ds_read2_b64 v[22:25], v8 offset0:32 offset1:48
	ds_read_b128 v[26:29], v9
	ds_read_b128 v[30:33], v9 offset:16
	s_add_i32 s4, s4, 32
	v_add_u32_e32 v8, 0x200, v8
	v_add_u32_e32 v7, 0x420, v7
	s_waitcnt lgkmcnt(1)
	v_mul_f32_e32 v34, v27, v11
	v_mul_f32_e32 v35, v26, v11
	v_mul_f32_e32 v36, v29, v13
	v_mul_f32_e32 v37, v28, v13
	v_fma_f32 v34, v26, v10, -v34
	v_fma_f32 v35, v27, v10, v35
	v_fma_f32 v36, v28, v12, -v36
	v_fma_f32 v37, v29, v12, v37
	s_waitcnt lgkmcnt(0)
	v_mul_f32_e32 v38, v31, v19
	v_mul_f32_e32 v39, v30, v19
	v_mul_f32_e32 v40, v33, v21
	v_mul_f32_e32 v41, v32, v21
	v_fma_f32 v38, v30, v18, -v38
	v_fma_f32 v39, v31, v18, v39
	v_fma_f32 v40, v32, v20, -v40
	v_fma_f32 v41, v33, v20, v41
	v_fma_f32 v6, v14, v34, v6
	v_fma_f32 v6, -v15, v35, v6
	v_fma_f32 v6, v16, v36, v6
	v_fma_f32 v6, -v17, v37, v6
	v_fma_f32 v6, v22, v38, v6
	v_fma_f32 v6, -v23, v39, v6
	v_fma_f32 v6, v24, v40, v6
	s_cmpk_eq_i32 s4, 0x200
	v_fma_f32 v6, -v25, v41, v6
	s_cbranch_scc0 .LBB0_88
	v_lshl_add_u32 v7, s6, 9, v1
	v_cmp_gt_u32_e64 s[4:5], 64, v7
	s_and_b64 s[18:19], vcc, s[4:5]
	s_and_saveexec_b64 s[4:5], s[18:19]
	s_cbranch_execz .LBB0_86
	global_load_dword v8, v[2:3], off nt
	s_waitcnt vmcnt(0)
	v_add_f32_e32 v6, v6, v8
	s_branch .LBB0_86
